# gu GEMM: LDS stage image changed so each LDS-DMA instruction fetches 8 full 128-B rows (8 lanes per row), swizzle (r>>1)&7, k=1 fragment reads via base^64
# baseline (speedup 1.0000x reference)
; DI int otid() { int t = threadIdx.x; asm volatile("" : "+v"(t)); return t; }
; #define PG8_STAGE(bufoff, gbase, voff) do { _Pragma("unroll") for (int _i = 0; _i < 2; ++_i) \
;     __builtin_amdgcn_global_load_lds((const unsigned*)((const char*)(gbase) + (voff)[_i]), (PG8_LAS unsigned*)(lds + (bufoff) + ldsw + _i * 8192), 16, 0, 0); } while (0)
; #define PG8_WAIT_V(n) asm volatile("s_waitcnt vmcnt(" #n ")" ::: "memory")
; #define PG8_BAR __builtin_amdgcn_s_barrier()
; template <class Epi>
; DI void gemm_phase(PG8_LAS unsigned char* lds, const Gemm g, const StaticOrder& S, const Epi& E) {
;   const int tid = otid(), wid = __builtin_amdgcn_readfirstlane(tid >> 6), lane = tid & 63, wr = wid >> 2, wc = wid & 3, fr = lane & 15, fq = lane >> 4;
;   const int K = g.K, nt = K / BK;
;   unsigned voffA[2], voffB[2];
; #pragma unroll
;   for (int i = 0; i < 2; ++i) { int R, C; stage_rc(tid * 16 + i * 8192, R, C); const int Rb = Epi::PERM ? ((R & ~31) + perm32(R & 31)) : R;
;     voffA[i] = (unsigned)(R * g.lda + C) * 2u; voffB[i] = (unsigned)(Rb * K + C) * 2u; }
;   const size_t kstep = (size_t)(BK * 2);
;   const size_t hstepA = (size_t)HALF * g.lda * 2, hstepB = (size_t)HALF * K * 2;
;   const size_t tstepA = 2 * hstepA, tstepB = 2 * hstepB;
;   const unsigned ldsw = (unsigned)wid * 1024u;
;   const int aoff = lds_byte(wr * 64 + fr, fq * 8), boff = lds_byte(wc * 32 + fr, fq * 8);
;     ...
;   Unit cur, nxt; int ui = 0;
;   if (!S.next(0, cur)) return;
;   f32x4 acc[2][2][4][2];
; #pragma unroll
;   for (int a = 0; a < 2; ++a)
; #pragma unroll
;     for (int b = 0; b < 2; ++b)
; #pragma unroll
;       for (int m = 0; m < 4; ++m)
; #pragma unroll
;         for (int n = 0; n < 2; ++n) acc[a][b][m][n] = (f32x4){0.f, 0.f, 0.f, 0.f};
;   bf16x8 At[4][2], B0[2][2], B1[2][2];
;   const char* cA = (const char*)g.A + (size_t)cur.pm * tstepA; const char* cB = (const char*)g.Bt + (size_t)cur.pn * tstepB;
;   PG8_STAGE(PG8_SB(0, 0), cB, voffB); PG8_STAGE(PG8_SA(0, 0), cA, voffA); PG8_STAGE(PG8_SB(0, 1), cB + hstepB, voffB); PG8_STAGE(PG8_SA(0, 1), cA + hstepA, voffA);
;   if (wr == 1) PG8_BAR;
;   PG8_WAIT_V(4); PG8_BAR;
;   PG8_STAGE(PG8_SB(1, 0), cB + kstep, voffB); PG8_STAGE(PG8_SA(1, 0), cA + kstep, voffA); PG8_STAGE(PG8_SB(1, 1), cB + hstepB + kstep, voffB);
;   PG8_WAIT_V(6); PG8_BAR;
.LBB0_45:
	s_or_b64 exec, exec, s[30:31]
	v_readlane_b32 s30, v252, 6
	v_mov_b32_e32 v4, v200
	v_readlane_b32 s31, v252, 7
	s_waitcnt lgkmcnt(0)
	s_barrier
	s_andn2_b64 vcc, exec, s[30:31]
	v_readfirstlane_b32 s28, v4
	s_cbranch_vccnz .LBB0_57
	v_lshlrev_b32_e32 v0, 4, v4
	v_add_u32_e32 v3, 0x2000, v0
	v_ashrrev_i32_e32 v2, 31, v3
	v_lshrrev_b32_e32 v2, 22, v2
	v_add_u32_e32 v2, v3, v2
	v_ashrrev_i32_e32 v2, 10, v2
	v_lshlrev_b32_e32 v5, 5, v2
	v_and_b32_e32 v6, 32, v5
	v_mul_i32_i24_e32 v5, 0x400, v2
	v_sub_u32_e32 v3, v3, v5
	v_lshrrev_b32_e32 v5, 4, v3
	v_bitop3_b32 v5, v5, v3, 32 bitop3:0x6c
	v_ashrrev_i32_e32 v3, 31, v5
	v_lshrrev_b32_e32 v3, 26, v3
	v_add_u32_e32 v7, v5, v3
	v_ashrrev_i32_e32 v3, 6, v7
	v_and_b32_e32 v7, 0xc0, v7
	v_sub_u32_e32 v5, v5, v7
	v_ashrrev_i16_sdwa v5, v202, sext(v5) dst_sel:DWORD dst_unused:UNUSED_PAD src0_sel:DWORD src1_sel:BYTE_0
	v_lshlrev_b32_e32 v7, 3, v2
	v_bfe_i32 v5, v5, 0, 16
	v_and_b32_e32 v7, 0x1ffff0, v7
	v_add_u32_e32 v6, v6, v5
	v_add_lshl_u32 v7, v3, v7, 11
	v_lshl_add_u32 v130, v6, 1, v7
	v_ashrrev_i32_e32 v6, 31, v4
	v_lshrrev_b32_e32 v6, 26, v6
	v_add_u32_e32 v6, v4, v6
	v_ashrrev_i32_e32 v6, 6, v6
	v_lshlrev_b32_e32 v7, 5, v6
	v_and_b32_e32 v9, 32, v7
	v_bfe_i32 v7, v4, 27, 1
	v_lshrrev_b32_e32 v7, 22, v7
	v_add_u32_e32 v7, v0, v7
	v_and_b32_e32 v7, 0xfffffc00, v7
	v_sub_u32_e32 v0, v0, v7
	v_lshrrev_b32_e32 v7, 4, v0
	v_bitop3_b32 v8, v7, v0, 32 bitop3:0x6c
	v_ashrrev_i32_e32 v0, 31, v0
	v_lshrrev_b32_e32 v0, 26, v0
	v_add_u32_e32 v0, v8, v0
	v_ashrrev_i32_e32 v7, 6, v0
	v_mul_i32_i24_e32 v0, 64, v7
	v_sub_u32_e32 v0, v8, v0
	v_ashrrev_i16_sdwa v0, v202, sext(v0) dst_sel:DWORD dst_unused:UNUSED_PAD src0_sel:DWORD src1_sel:BYTE_0
	v_bfe_i32 v8, v0, 0, 16
	s_ashr_i32 s30, s28, 6
	v_add_u32_e32 v0, v9, v8
	v_lshlrev_b32_e32 v9, 3, v6
	s_lshl_b32 s34, s30, 10
	v_and_b32_e32 v9, 0x1ffff0, v9
	v_add_lshl_u32 v9, v7, v9, 11
	s_add_i32 s37, s34, 0
	v_readlane_b32 s40, v252, 19
	v_lshl_add_u32 v0, v0, 1, v9
	v_lshrrev_b32_e32 v10, 3, v4
	v_lshrrev_b32_e32 v11, 4, v4
	v_and_b32_e32 v11, 7, v11
	v_and_b32_e32 v12, 7, v4
	v_xor_b32_e32 v12, v12, v11
	v_lshlrev_b32_e32 v12, 4, v12
	v_lshl_add_u32 v0, v10, 11, v12
	v_add_u32_e32 v130, 0x20000, v0
	s_add_i32 m0, s37, 0x10000
	v_readlane_b32 s41, v252, 20
	s_add_i32 s62, s37, 0x2000
	s_add_i32 s63, s37, 0x4000
	s_add_i32 s64, s37, 0x6000
	s_ashr_i32 s31, s28, 8
	s_nop 0
	global_load_lds_dwordx4 v0, s[40:41]
	s_add_i32 m0, s37, 0x12000
	s_nop 0
	global_load_lds_dwordx4 v130, s[40:41]
	v_readlane_b32 s40, v252, 15
	s_mov_b32 m0, s37
	v_readlane_b32 s41, v252, 16
	s_nop 4
	global_load_lds_dwordx4 v0, s[40:41]
	s_mov_b32 m0, s62
	s_nop 0
	global_load_lds_dwordx4 v130, s[40:41]
	v_readlane_b32 s40, v252, 13
	s_add_i32 m0, s37, 0x14000
	v_readlane_b32 s41, v252, 14
	s_nop 4
	global_load_lds_dwordx4 v0, s[40:41]
	s_add_i32 m0, s37, 0x16000
	s_cmp_lg_u32 s31, 1
	global_load_lds_dwordx4 v130, s[40:41]
	v_readlane_b32 s40, v252, 17
	s_mov_b32 m0, s63
	v_readlane_b32 s41, v252, 18
	s_nop 4
	global_load_lds_dwordx4 v0, s[40:41]
	s_mov_b32 m0, s64
	s_nop 0
	global_load_lds_dwordx4 v130, s[40:41]
	s_cbranch_scc1 .LBB0_48
	s_barrier
	s_setprio 1
.LBB0_48:
	v_readlane_b32 s58, v252, 19
	v_readlane_b32 s59, v252, 20
	v_mov_b32_e32 v131, v1
	v_readlane_b32 s56, v252, 15
	v_lshl_add_u64 v[10:11], s[58:59], 0, v[0:1]
	v_lshl_add_u64 v[12:13], s[58:59], 0, v[130:131]
	v_readlane_b32 s57, v252, 16
	s_add_i32 m0, s37, 0x18000
	v_lshl_add_u64 v[10:11], v[10:11], 0, s[86:87]
	v_lshl_add_u64 v[14:15], s[56:57], 0, v[0:1]
	s_waitcnt vmcnt(4)
	s_barrier
	global_load_lds_dwordx4 v[10:11], off
	v_lshl_add_u64 v[10:11], v[12:13], 0, s[86:87]
	s_add_i32 m0, s37, 0x1a000
	s_add_i32 s65, s37, 0x8000
	v_lshl_add_u64 v[16:17], s[56:57], 0, v[130:131]
	global_load_lds_dwordx4 v[10:11], off
	v_lshl_add_u64 v[10:11], v[14:15], 0, s[86:87]
	s_mov_b32 m0, s65
	s_add_i32 s66, s37, 0xa000
	v_readlane_b32 s40, v252, 21
	global_load_lds_dwordx4 v[10:11], off
	v_lshl_add_u64 v[10:11], v[16:17], 0, s[86:87]
	s_mov_b32 m0, s66
	v_readlane_b32 s41, v252, 22
	global_load_lds_dwordx4 v[10:11], off
	s_add_i32 m0, s37, 0x1c000
	v_lshl_add_u64 v[10:11], s[40:41], 0, v[0:1]
	global_load_lds_dwordx4 v[10:11], off
	v_lshl_add_u64 v[10:11], s[40:41], 0, v[130:131]
	s_add_i32 m0, s37, 0x1e000
	v_and_b32_e32 v9, 15, v4
	global_load_lds_dwordx4 v[10:11], off
	v_bfe_u32 v4, v4, 4, 2
	v_lshlrev_b32_e32 v10, 4, v4
	v_lshlrev_b32_e32 v151, 2, v4
	v_lshlrev_b32_e32 v4, 14, v6
	s_lshl_b32 s30, s30, 5
	v_and_b32_e32 v4, 0xffff8000, v4
	v_lshl_or_b32 v148, s31, 6, v9
	v_lshl_or_b32 v10, v9, 6, v10
	v_lshlrev_b32_e32 v9, 2, v9
	s_and_b32 s67, s30, 0x60
	v_lshl_add_u32 v4, v7, 11, v4
	v_and_b32_e32 v6, 1, v6
	v_and_b32_e32 v11, 32, v9
	s_lshl_b32 s30, s67, 7
	v_lshl_or_b32 v4, v6, 6, v4
	v_bitop3_b32 v149, v10, s30, v11 bitop3:0xde
	s_lshl_b32 s30, s31, 8
	v_lshl_add_u32 v132, v8, 1, v4
	v_lshlrev_b32_e32 v4, 14, v2
	s_add_i32 s30, s30, 0
	v_and_b32_e32 v4, 0xffff8000, v4
	s_lshl_b32 s40, s31, 13
	s_waitcnt vmcnt(6)
	s_add_i32 s30, s30, 0x20000
	v_lshl_add_u32 v3, v3, 11, v4
	v_and_b32_e32 v2, 1, v2
	v_bitop3_b32 v12, v10, s40, v11 bitop3:0xde
	v_add_u32_e32 v150, s30, v9
	v_lshl_or_b32 v2, v2, 6, v3
	v_readlane_b32 s30, v252, 9
	v_mov_b32_e32 v133, v1
	v_lshl_add_u32 v142, v5, 1, v2
	v_mov_b32_e32 v143, v1
	s_mov_b32 s69, 0
	v_add_u32_e32 v152, 0, v12
	v_readlane_b32 s70, v252, 8
	s_mov_b32 s71, s30
	v_mov_b32_e32 v132, v0
	v_mov_b32_e32 v142, v130
	v_and_b32_e32 v10, 15, v204
	v_lshrrev_b32_e32 v11, 4, v204
	v_bfe_u32 v12, v10, 1, 3
	v_xor_b32_e32 v11, v11, v12
	v_lshlrev_b32_e32 v11, 4, v11
	v_and_b32_e32 v12, 7, v10
	v_lshl_or_b32 v11, v12, 7, v11
	v_lshrrev_b32_e32 v12, 3, v10
	v_lshl_or_b32 v11, v12, 10, v11
	v_and_b32_e32 v149, 0xfffff000, v149
	v_or_b32_e32 v149, v149, v11
	v_and_b32_e32 v152, 0xfffff000, v152
	v_or_b32_e32 v152, v152, v11
	v_xor_b32_e32 v244, 64, v152
	v_xor_b32_e32 v245, 64, v149
	s_barrier
	v_readlane_b32 s31, v252, 10

; #define PG8_STAGE(bufoff, gbase, voff) do { _Pragma("unroll") for (int _i = 0; _i < 2; ++_i) \
;     __builtin_amdgcn_global_load_lds((const unsigned*)((const char*)(gbase) + (voff)[_i]), (PG8_LAS unsigned*)(lds + (bufoff) + ldsw + _i * 8192), 16, 0, 0); } while (0)
; #define PG8_LDA(dst, b, h) do { _Pragma("unroll") for (int m = 0; m < 4; ++m) _Pragma("unroll") for (int k = 0; k < 2; ++k) dst[m][k] = *(const PG8_LAS bf16x8*)(lds + PG8_SA(b, h) + aoff + m * 2048 + k * 1024); } while (0)
; #define PG8_LDB(dst, b, h) do { _Pragma("unroll") for (int n = 0; n < 2; ++n) _Pragma("unroll") for (int k = 0; k < 2; ++k) dst[n][k] = *(const PG8_LAS bf16x8*)(lds + PG8_SB(b, h) + boff + n * 2048 + k * 1024); } while (0)
; #define PG8_MMA(ai, bj, At, Bt) do { __builtin_amdgcn_s_setprio(1); _Pragma("unroll") for (int m = 0; m < 4; ++m) _Pragma("unroll") for (int n = 0; n < 2; ++n) _Pragma("unroll") for (int k = 0; k < 2; ++k) \
;     acc[ai][bj][m][n] = __builtin_amdgcn_mfma_f32_16x16x32_bf16(Bt[n][k], At[m][k], acc[ai][bj][m][n], 0, 0, 0); __builtin_amdgcn_s_setprio(0); } while (0)
; #define PG8_WAIT_L(n) asm volatile("s_waitcnt lgkmcnt(" #n ")" ::: "memory")
; #define PG8_BAR __builtin_amdgcn_s_barrier()
; #define PG8_SCHED __builtin_amdgcn_sched_barrier(0)
; template <class Epi>
; DI void gemm_phase(PG8_LAS unsigned char* lds, const Gemm g, const StaticOrder& S, const Epi& E) {
;     ...
;     for (int t = 0; t < nt; t += 2) {
;       const bool last = (t == nt - 2);
;       const char* a1 = cA + (size_t)(t + 1) * kstep;
;       const char* a2 = last ? nA : cA + (size_t)(t + 2) * kstep; const char* b2 = last ? nB : cB + (size_t)(t + 2) * kstep;
;       const char* a3 = a2 + kstep; const char* b3 = b2 + kstep;
;       PG8_LDB(B0, 0, 0); PG8_SCHED; PG8_LDA(At, 0, 0); PG8_STAGE(PG8_SA(1, 1), a1 + hstepA, voffA);
;       PG8_WAIT_L(8); PG8_BAR; PG8_WAIT_L(0); PG8_MMA(0, 0, At, B0); PG8_BAR; PG8_SCHED;
;       PG8_LDB(B1, 0, 1); PG8_STAGE(PG8_SB(0, 0), b2, voffB);
;       PG8_BAR; PG8_WAIT_L(0); PG8_MMA(0, 1, At, B1); PG8_BAR;
;       PG8_LDA(At, 0, 1); PG8_STAGE(PG8_SA(0, 0), a2, voffA);
;       PG8_BAR; PG8_WAIT_L(0); PG8_MMA(1, 0, At, B0); PG8_BAR; PG8_SCHED;
.LBB0_52:
	s_add_u32 s58, s56, 0xfffc0080
	s_addc_u32 s59, s57, -1
	s_add_i32 s77, 0, 0x10000
	v_add_u32_e32 v153, s77, v149
	v_add_u32_e32 v246, s77, v245
	ds_read_b128 v[144:147], v153
	ds_read_b128 v[154:157], v246
	ds_read_b128 v[158:161], v153 offset:2048
	ds_read_b128 v[162:165], v246 offset:2048
	s_cmp_eq_u32 s76, 12
	s_cselect_b32 s61, s51, s59
	s_cselect_b32 s60, s72, s58
	s_cselect_b32 s59, s31, s75
	s_cselect_b32 s58, s73, s74
	v_lshl_add_u64 v[198:199], s[56:57], 0, v[132:133]
	s_add_i32 m0, s37, 0xc000
	ds_read_b128 v[166:169], v152
	ds_read_b128 v[170:173], v244
	ds_read_b128 v[174:177], v152 offset:2048
	ds_read_b128 v[178:181], v244 offset:2048
	ds_read_b128 v[182:185], v152 offset:4096
	ds_read_b128 v[186:189], v244 offset:4096
	ds_read_b128 v[190:193], v152 offset:6144
	ds_read_b128 v[194:197], v244 offset:6144
	global_load_lds_dwordx4 v[198:199], off
	v_lshl_add_u64 v[198:199], s[56:57], 0, v[142:143]
	s_add_i32 m0, s37, 0xe000
	s_nop 0
	global_load_lds_dwordx4 v[198:199], off
	s_waitcnt lgkmcnt(8)
	s_barrier
	s_waitcnt lgkmcnt(0)
	s_waitcnt lgkmcnt(0)
	v_mfma_f32_16x16x32_bf16 v[126:129], v[144:147], v[166:169], v[126:129]
	v_mfma_f32_16x16x32_bf16 v[122:125], v[158:161], v[166:169], v[122:125]
	v_mfma_f32_16x16x32_bf16 v[110:113], v[144:147], v[174:177], v[110:113]
	v_mfma_f32_16x16x32_bf16 v[106:109], v[158:161], v[174:177], v[106:109]
	v_mfma_f32_16x16x32_bf16 v[94:97], v[144:147], v[182:185], v[94:97]
	v_mfma_f32_16x16x32_bf16 v[90:93], v[158:161], v[182:185], v[90:93]
	v_mfma_f32_16x16x32_bf16 v[78:81], v[144:147], v[190:193], v[78:81]
	v_mfma_f32_16x16x32_bf16 v[74:77], v[158:161], v[190:193], v[74:77]
	v_mfma_f32_16x16x32_bf16 v[126:129], v[154:157], v[170:173], v[126:129]
	v_mfma_f32_16x16x32_bf16 v[122:125], v[162:165], v[170:173], v[122:125]
	v_mfma_f32_16x16x32_bf16 v[110:113], v[154:157], v[178:181], v[110:113]
	v_mfma_f32_16x16x32_bf16 v[106:109], v[162:165], v[178:181], v[106:109]
	v_mfma_f32_16x16x32_bf16 v[94:97], v[154:157], v[186:189], v[94:97]
	v_mfma_f32_16x16x32_bf16 v[90:93], v[162:165], v[186:189], v[90:93]
	v_mfma_f32_16x16x32_bf16 v[78:81], v[154:157], v[194:197], v[78:81]
	v_mfma_f32_16x16x32_bf16 v[74:77], v[162:165], v[194:197], v[74:77]
	s_barrier
	s_add_i32 s80, 0, 0x14000
	s_add_i32 s77, s77, s34
	v_add_u32_e32 v153, s80, v149
	v_add_u32_e32 v246, s80, v245
	v_lshl_add_u64 v[198:199], s[58:59], 0, v[0:1]
	s_mov_b32 m0, s77
	ds_read_b128 v[222:225], v153
	ds_read_b128 v[226:229], v246
	ds_read_b128 v[230:233], v153 offset:2048
	ds_read_b128 v[234:237], v246 offset:2048
	global_load_lds_dwordx4 v[198:199], off
	v_lshl_add_u64 v[238:239], s[58:59], 0, v[130:131]
	s_add_i32 m0, s77, 0x2000
	s_nop 0
	global_load_lds_dwordx4 v[238:239], off
	s_barrier
	s_waitcnt lgkmcnt(0)
	s_waitcnt lgkmcnt(0)
	v_mfma_f32_16x16x32_bf16 v[118:121], v[222:225], v[166:169], v[118:121]
	v_mfma_f32_16x16x32_bf16 v[114:117], v[230:233], v[166:169], v[114:117]
	v_mfma_f32_16x16x32_bf16 v[102:105], v[222:225], v[174:177], v[102:105]
	v_mfma_f32_16x16x32_bf16 v[98:101], v[230:233], v[174:177], v[98:101]
	v_mfma_f32_16x16x32_bf16 v[86:89], v[222:225], v[182:185], v[86:89]
	v_mfma_f32_16x16x32_bf16 v[82:85], v[230:233], v[182:185], v[82:85]
	v_mfma_f32_16x16x32_bf16 v[70:73], v[222:225], v[190:193], v[70:73]
	v_mfma_f32_16x16x32_bf16 v[66:69], v[230:233], v[190:193], v[66:69]
	v_mfma_f32_16x16x32_bf16 v[118:121], v[226:229], v[170:173], v[118:121]
	v_mfma_f32_16x16x32_bf16 v[114:117], v[234:237], v[170:173], v[114:117]
	v_mfma_f32_16x16x32_bf16 v[102:105], v[226:229], v[178:181], v[102:105]
	v_mfma_f32_16x16x32_bf16 v[98:101], v[234:237], v[178:181], v[98:101]
	v_mfma_f32_16x16x32_bf16 v[86:89], v[226:229], v[186:189], v[86:89]
	v_mfma_f32_16x16x32_bf16 v[82:85], v[234:237], v[186:189], v[82:85]
	v_mfma_f32_16x16x32_bf16 v[70:73], v[226:229], v[194:197], v[70:73]
	v_mfma_f32_16x16x32_bf16 v[66:69], v[234:237], v[194:197], v[66:69]
	s_mov_b32 m0, s37
	v_lshl_add_u64 v[240:241], s[60:61], 0, v[0:1]
	s_barrier
	ds_read_b128 v[166:169], v152 offset:16384
	ds_read_b128 v[170:173], v244 offset:16384
	ds_read_b128 v[174:177], v152 offset:18432
	ds_read_b128 v[178:181], v244 offset:18432
	ds_read_b128 v[182:185], v152 offset:20480
	ds_read_b128 v[186:189], v244 offset:20480
	ds_read_b128 v[190:193], v152 offset:22528
	ds_read_b128 v[194:197], v244 offset:22528
	global_load_lds_dwordx4 v[240:241], off
	v_lshl_add_u64 v[242:243], s[60:61], 0, v[130:131]
	s_mov_b32 m0, s62
	s_nop 0
	global_load_lds_dwordx4 v[242:243], off
	s_barrier
	s_waitcnt lgkmcnt(0)
	s_waitcnt lgkmcnt(0)
	v_mfma_f32_16x16x32_bf16 v[62:65], v[144:147], v[166:169], v[62:65]
	v_mfma_f32_16x16x32_bf16 v[58:61], v[158:161], v[166:169], v[58:61]
	v_mfma_f32_16x16x32_bf16 v[46:49], v[144:147], v[174:177], v[46:49]
	v_mfma_f32_16x16x32_bf16 v[42:45], v[158:161], v[174:177], v[42:45]
	v_mfma_f32_16x16x32_bf16 v[30:33], v[144:147], v[182:185], v[30:33]
	v_mfma_f32_16x16x32_bf16 v[26:29], v[158:161], v[182:185], v[26:29]
	v_mfma_f32_16x16x32_bf16 v[14:17], v[144:147], v[190:193], v[14:17]
	v_mfma_f32_16x16x32_bf16 v[10:13], v[158:161], v[190:193], v[10:13]
	v_mfma_f32_16x16x32_bf16 v[62:65], v[154:157], v[170:173], v[62:65]
	v_mfma_f32_16x16x32_bf16 v[58:61], v[162:165], v[170:173], v[58:61]
	v_mfma_f32_16x16x32_bf16 v[46:49], v[154:157], v[178:181], v[46:49]
	v_mfma_f32_16x16x32_bf16 v[42:45], v[162:165], v[178:181], v[42:45]
	v_mfma_f32_16x16x32_bf16 v[30:33], v[154:157], v[186:189], v[30:33]
	v_mfma_f32_16x16x32_bf16 v[26:29], v[162:165], v[186:189], v[26:29]
	v_mfma_f32_16x16x32_bf16 v[14:17], v[154:157], v[194:197], v[14:17]
	v_mfma_f32_16x16x32_bf16 v[10:13], v[162:165], v[194:197], v[10:13]
	s_barrier
; #define PG8_STAGE(bufoff, gbase, voff) do { _Pragma("unroll") for (int _i = 0; _i < 2; ++_i) \
;     __builtin_amdgcn_global_load_lds((const unsigned*)((const char*)(gbase) + (voff)[_i]), (PG8_LAS unsigned*)(lds + (bufoff) + ldsw + _i * 8192), 16, 0, 0); } while (0)
; #define PG8_LDA(dst, b, h) do { _Pragma("unroll") for (int m = 0; m < 4; ++m) _Pragma("unroll") for (int k = 0; k < 2; ++k) dst[m][k] = *(const PG8_LAS bf16x8*)(lds + PG8_SA(b, h) + aoff + m * 2048 + k * 1024); } while (0)
; #define PG8_LDB(dst, b, h) do { _Pragma("unroll") for (int n = 0; n < 2; ++n) _Pragma("unroll") for (int k = 0; k < 2; ++k) dst[n][k] = *(const PG8_LAS bf16x8*)(lds + PG8_SB(b, h) + boff + n * 2048 + k * 1024); } while (0)
; #define PG8_MMA(ai, bj, At, Bt) do { __builtin_amdgcn_s_setprio(1); _Pragma("unroll") for (int m = 0; m < 4; ++m) _Pragma("unroll") for (int n = 0; n < 2; ++n) _Pragma("unroll") for (int k = 0; k < 2; ++k) \
;     acc[ai][bj][m][n] = __builtin_amdgcn_mfma_f32_16x16x32_bf16(Bt[n][k], At[m][k], acc[ai][bj][m][n], 0, 0, 0); __builtin_amdgcn_s_setprio(0); } while (0)
; #define PG8_WAIT_V(n) asm volatile("s_waitcnt vmcnt(" #n ")" ::: "memory")
; #define PG8_WAIT_L(n) asm volatile("s_waitcnt lgkmcnt(" #n ")" ::: "memory")
; #define PG8_BAR __builtin_amdgcn_s_barrier()
; #define PG8_SCHED __builtin_amdgcn_sched_barrier(0)
; template <class Epi>
; DI void gemm_phase(PG8_LAS unsigned char* lds, const Gemm g, const StaticOrder& S, const Epi& E) {
;     ...
;       PG8_STAGE(PG8_SB(0, 1), b2 + hstepB, voffB);
;       PG8_WAIT_V(6); PG8_BAR; PG8_MMA(1, 1, At, B1); PG8_BAR;
;       PG8_LDB(B0, 1, 0); PG8_SCHED; PG8_LDA(At, 1, 0); PG8_STAGE(PG8_SA(0, 1), a2 + hstepA, voffA);
;       PG8_WAIT_L(8); PG8_BAR; PG8_WAIT_L(0); PG8_MMA(0, 0, At, B0); PG8_BAR; PG8_SCHED;
;       PG8_LDB(B1, 1, 1); PG8_STAGE(PG8_SB(1, 0), b3, voffB);
;       PG8_BAR; PG8_WAIT_L(0); PG8_MMA(0, 1, At, B1); PG8_BAR;
;       PG8_LDA(At, 1, 1); PG8_STAGE(PG8_SA(1, 0), a3, voffA);
	s_add_u32 s78, s58, 0x40000
	s_addc_u32 s79, s59, 0
	s_add_i32 s77, s80, s34
	v_lshl_add_u64 v[144:145], s[78:79], 0, v[0:1]
	s_mov_b32 m0, s77
	s_nop 0
	global_load_lds_dwordx4 v[144:145], off
	v_lshl_add_u64 v[144:145], s[78:79], 0, v[130:131]
	s_add_i32 m0, s77, 0x2000
	s_nop 0
	global_load_lds_dwordx4 v[144:145], off
	s_waitcnt vmcnt(6)
	s_barrier
	v_mfma_f32_16x16x32_bf16 v[54:57], v[222:225], v[166:169], v[54:57]
	v_mfma_f32_16x16x32_bf16 v[50:53], v[230:233], v[166:169], v[50:53]
	v_mfma_f32_16x16x32_bf16 v[38:41], v[222:225], v[174:177], v[38:41]
	v_mfma_f32_16x16x32_bf16 v[34:37], v[230:233], v[174:177], v[34:37]
	v_mfma_f32_16x16x32_bf16 v[22:25], v[222:225], v[182:185], v[22:25]
	v_mfma_f32_16x16x32_bf16 v[18:21], v[230:233], v[182:185], v[18:21]
	v_mfma_f32_16x16x32_bf16 v[6:9], v[222:225], v[190:193], v[6:9]
	v_mfma_f32_16x16x32_bf16 v[2:5], v[230:233], v[190:193], v[2:5]
	v_mfma_f32_16x16x32_bf16 v[54:57], v[226:229], v[170:173], v[54:57]
	v_mfma_f32_16x16x32_bf16 v[50:53], v[234:237], v[170:173], v[50:53]
	v_mfma_f32_16x16x32_bf16 v[38:41], v[226:229], v[178:181], v[38:41]
	v_mfma_f32_16x16x32_bf16 v[34:37], v[234:237], v[178:181], v[34:37]
	v_mfma_f32_16x16x32_bf16 v[22:25], v[226:229], v[186:189], v[22:25]
	v_mfma_f32_16x16x32_bf16 v[18:21], v[234:237], v[186:189], v[18:21]
	v_mfma_f32_16x16x32_bf16 v[6:9], v[226:229], v[194:197], v[6:9]
	v_mfma_f32_16x16x32_bf16 v[2:5], v[234:237], v[194:197], v[2:5]
	s_add_i32 s77, 0, 0x18000
	v_add_u32_e32 v153, s77, v149
	v_add_u32_e32 v246, s77, v245
	s_barrier
	ds_read_b128 v[144:147], v153
	ds_read_b128 v[154:157], v246
	ds_read_b128 v[158:161], v153 offset:2048
	ds_read_b128 v[162:165], v246 offset:2048
	s_add_u32 s60, s60, 0x40000
	s_addc_u32 s61, s61, 0
	s_mov_b32 m0, s63
	v_lshl_add_u64 v[222:223], s[60:61], 0, v[0:1]
	ds_read_b128 v[166:169], v152 offset:32768
	ds_read_b128 v[170:173], v244 offset:32768
	ds_read_b128 v[174:177], v152 offset:34816
	ds_read_b128 v[178:181], v244 offset:34816
	ds_read_b128 v[182:185], v152 offset:36864
	ds_read_b128 v[186:189], v244 offset:36864
	ds_read_b128 v[190:193], v152 offset:38912
	ds_read_b128 v[194:197], v244 offset:38912
	global_load_lds_dwordx4 v[222:223], off
	v_lshl_add_u64 v[222:223], s[60:61], 0, v[130:131]
	s_mov_b32 m0, s64
	s_nop 0
	global_load_lds_dwordx4 v[222:223], off
	s_waitcnt lgkmcnt(8)
	s_barrier
	s_waitcnt lgkmcnt(0)
	s_waitcnt lgkmcnt(0)
	v_mfma_f32_16x16x32_bf16 v[126:129], v[144:147], v[166:169], v[126:129]
	v_mfma_f32_16x16x32_bf16 v[122:125], v[158:161], v[166:169], v[122:125]
	v_mfma_f32_16x16x32_bf16 v[110:113], v[144:147], v[174:177], v[110:113]
	v_mfma_f32_16x16x32_bf16 v[106:109], v[158:161], v[174:177], v[106:109]
	v_mfma_f32_16x16x32_bf16 v[94:97], v[144:147], v[182:185], v[94:97]
	v_mfma_f32_16x16x32_bf16 v[90:93], v[158:161], v[182:185], v[90:93]
	v_mfma_f32_16x16x32_bf16 v[78:81], v[144:147], v[190:193], v[78:81]
	v_mfma_f32_16x16x32_bf16 v[74:77], v[158:161], v[190:193], v[74:77]
	v_mfma_f32_16x16x32_bf16 v[126:129], v[154:157], v[170:173], v[126:129]
	v_mfma_f32_16x16x32_bf16 v[122:125], v[162:165], v[170:173], v[122:125]
	v_mfma_f32_16x16x32_bf16 v[110:113], v[154:157], v[178:181], v[110:113]
	v_mfma_f32_16x16x32_bf16 v[106:109], v[162:165], v[178:181], v[106:109]
	v_mfma_f32_16x16x32_bf16 v[94:97], v[154:157], v[186:189], v[94:97]
	v_mfma_f32_16x16x32_bf16 v[90:93], v[162:165], v[186:189], v[90:93]
	v_mfma_f32_16x16x32_bf16 v[78:81], v[154:157], v[194:197], v[78:81]
	v_mfma_f32_16x16x32_bf16 v[74:77], v[162:165], v[194:197], v[74:77]
	s_barrier
	s_add_i32 s60, 0, 0x1c000
	s_add_i32 s61, s77, s34
	v_add_u32_e32 v153, s60, v149
	v_add_u32_e32 v246, s60, v245
	v_lshl_add_u64 v[198:199], v[198:199], 0, s[86:87]
	s_mov_b32 m0, s61
	ds_read_b128 v[222:225], v153
	ds_read_b128 v[226:229], v246
	ds_read_b128 v[230:233], v153 offset:2048
	ds_read_b128 v[234:237], v246 offset:2048
	global_load_lds_dwordx4 v[198:199], off
	v_lshl_add_u64 v[198:199], v[238:239], 0, s[86:87]
	s_add_i32 m0, s61, 0x2000
	s_nop 0
	global_load_lds_dwordx4 v[198:199], off
	s_barrier
	s_waitcnt lgkmcnt(0)
	s_waitcnt lgkmcnt(0)
	v_mfma_f32_16x16x32_bf16 v[118:121], v[222:225], v[166:169], v[118:121]
	v_mfma_f32_16x16x32_bf16 v[114:117], v[230:233], v[166:169], v[114:117]
	v_mfma_f32_16x16x32_bf16 v[102:105], v[222:225], v[174:177], v[102:105]
	v_mfma_f32_16x16x32_bf16 v[98:101], v[230:233], v[174:177], v[98:101]
	v_mfma_f32_16x16x32_bf16 v[86:89], v[222:225], v[182:185], v[86:89]
	v_mfma_f32_16x16x32_bf16 v[82:85], v[230:233], v[182:185], v[82:85]
	v_mfma_f32_16x16x32_bf16 v[70:73], v[222:225], v[190:193], v[70:73]
	v_mfma_f32_16x16x32_bf16 v[66:69], v[230:233], v[190:193], v[66:69]
	v_mfma_f32_16x16x32_bf16 v[118:121], v[226:229], v[170:173], v[118:121]
	v_mfma_f32_16x16x32_bf16 v[114:117], v[234:237], v[170:173], v[114:117]
	v_mfma_f32_16x16x32_bf16 v[102:105], v[226:229], v[178:181], v[102:105]
	v_mfma_f32_16x16x32_bf16 v[98:101], v[234:237], v[178:181], v[98:101]
	v_mfma_f32_16x16x32_bf16 v[86:89], v[226:229], v[186:189], v[86:89]
	v_mfma_f32_16x16x32_bf16 v[82:85], v[234:237], v[186:189], v[82:85]
	v_mfma_f32_16x16x32_bf16 v[70:73], v[226:229], v[194:197], v[70:73]
	v_mfma_f32_16x16x32_bf16 v[66:69], v[234:237], v[194:197], v[66:69]
	s_mov_b32 m0, s65
	v_lshl_add_u64 v[198:199], v[240:241], 0, s[86:87]
	s_barrier
	ds_read_b128 v[166:169], v152 offset:49152
	ds_read_b128 v[170:173], v244 offset:49152
	ds_read_b128 v[174:177], v152 offset:51200
	ds_read_b128 v[178:181], v244 offset:51200
	ds_read_b128 v[182:185], v152 offset:53248
	ds_read_b128 v[186:189], v244 offset:53248
	ds_read_b128 v[190:193], v152 offset:55296
	ds_read_b128 v[194:197], v244 offset:55296
	global_load_lds_dwordx4 v[198:199], off
	v_lshl_add_u64 v[198:199], v[242:243], 0, s[86:87]
	s_mov_b32 m0, s66
	s_nop 0
	global_load_lds_dwordx4 v[198:199], off
	s_barrier
; DI unsigned pk2(float lo, float hi) { f32x2 v = {lo, hi}; bf2_t r = __builtin_convertvector(v, bf2_t); return __builtin_bit_cast(unsigned, r); }
; DI float silu(float x) { return x * __builtin_amdgcn_rcpf(1.f + __expf(-x)); }
; #define PG8_LAS __attribute__((address_space(3)))
; #define PG8_STAGE(bufoff, gbase, voff) do { _Pragma("unroll") for (int _i = 0; _i < 2; ++_i) \
;     __builtin_amdgcn_global_load_lds((const unsigned*)((const char*)(gbase) + (voff)[_i]), (PG8_LAS unsigned*)(lds + (bufoff) + ldsw + _i * 8192), 16, 0, 0); } while (0)
; #define PG8_MMA(ai, bj, At, Bt) do { __builtin_amdgcn_s_setprio(1); _Pragma("unroll") for (int m = 0; m < 4; ++m) _Pragma("unroll") for (int n = 0; n < 2; ++n) _Pragma("unroll") for (int k = 0; k < 2; ++k) \
;     acc[ai][bj][m][n] = __builtin_amdgcn_mfma_f32_16x16x32_bf16(Bt[n][k], At[m][k], acc[ai][bj][m][n], 0, 0, 0); __builtin_amdgcn_s_setprio(0); } while (0)
; #define PG8_WAIT_V(n) asm volatile("s_waitcnt vmcnt(" #n ")" ::: "memory")
; #define PG8_WAIT_L(n) asm volatile("s_waitcnt lgkmcnt(" #n ")" ::: "memory")
; #define PG8_BAR __builtin_amdgcn_s_barrier()
; #define PG8_SCHED __builtin_amdgcn_sched_barrier(0)
;   DI void operator()(const f32x4 (&acc)[2][2][4][2], const Unit& u, int wr, int wc, int fr, int fq, const PG8_LAS float* sR) const {
;     const int row0 = u.pm * BM + wr * 64 + fr, j0 = (u.pn * BM + wc * 32) / 2 + 4 * fq;
; #pragma unroll
;     for (int ai = 0; ai < 2; ++ai)
; #pragma unroll
;       for (int m = 0; m < 4; ++m) {
;         bf16_t* rowp = Hd + (size_t)(row0 + ai * HALF + m * 16) * 2816 + j0;
;         const float rs = sR[ai * 128 + m * 16 + fr];
; #pragma unroll
;         for (int bj = 0; bj < 2; ++bj) {
;           const f32x4 g = acc[ai][bj][m][0] * rs, up = acc[ai][bj][m][1] * rs;
;           u32x2 o; o[0] = pk2(silu(g[0]) * up[0], silu(g[1]) * up[1]); o[1] = pk2(silu(g[2]) * up[2], silu(g[3]) * up[3]);
;           *(u32x2*)(rowp + bj * (HALF / 2)) = o;
;         }
;       }
; template <class Epi>
; DI void gemm_phase(PG8_LAS unsigned char* lds, const Gemm g, const StaticOrder& S, const Epi& E) {
;     ...
;       PG8_BAR; PG8_WAIT_L(0); PG8_MMA(1, 0, At, B0); PG8_BAR; PG8_SCHED;
;       PG8_STAGE(PG8_SB(1, 1), b3 + hstepB, voffB);
;       PG8_WAIT_V(6); PG8_BAR; PG8_MMA(1, 1, At, B1); PG8_BAR;
	s_waitcnt lgkmcnt(0)
	s_waitcnt lgkmcnt(0)
	v_mfma_f32_16x16x32_bf16 v[62:65], v[144:147], v[166:169], v[62:65]
	v_mfma_f32_16x16x32_bf16 v[58:61], v[158:161], v[166:169], v[58:61]
	v_mfma_f32_16x16x32_bf16 v[46:49], v[144:147], v[174:177], v[46:49]
	v_mfma_f32_16x16x32_bf16 v[42:45], v[158:161], v[174:177], v[42:45]
	v_mfma_f32_16x16x32_bf16 v[30:33], v[144:147], v[182:185], v[30:33]
	v_mfma_f32_16x16x32_bf16 v[26:29], v[158:161], v[182:185], v[26:29]
	v_mfma_f32_16x16x32_bf16 v[14:17], v[144:147], v[190:193], v[14:17]
	v_mfma_f32_16x16x32_bf16 v[10:13], v[158:161], v[190:193], v[10:13]
	v_mfma_f32_16x16x32_bf16 v[62:65], v[154:157], v[170:173], v[62:65]
	v_mfma_f32_16x16x32_bf16 v[58:61], v[162:165], v[170:173], v[58:61]
	v_mfma_f32_16x16x32_bf16 v[46:49], v[154:157], v[178:181], v[46:49]
	v_mfma_f32_16x16x32_bf16 v[42:45], v[162:165], v[178:181], v[42:45]
	v_mfma_f32_16x16x32_bf16 v[30:33], v[154:157], v[186:189], v[30:33]
	v_mfma_f32_16x16x32_bf16 v[26:29], v[162:165], v[186:189], v[26:29]
	v_mfma_f32_16x16x32_bf16 v[14:17], v[154:157], v[194:197], v[14:17]
	v_mfma_f32_16x16x32_bf16 v[10:13], v[162:165], v[194:197], v[10:13]
	s_barrier
	s_add_u32 s58, s58, 0x40080
	s_addc_u32 s59, s59, 0
	s_add_i32 s60, s60, s34
	v_lshl_add_u64 v[144:145], s[58:59], 0, v[0:1]
	s_mov_b32 m0, s60
	s_nop 0
	global_load_lds_dwordx4 v[144:145], off
	v_lshl_add_u64 v[144:145], s[58:59], 0, v[130:131]
	s_add_i32 m0, s60, 0x2000
	s_nop 0
	global_load_lds_dwordx4 v[144:145], off
	s_waitcnt vmcnt(6)
	s_barrier
	v_mfma_f32_16x16x32_bf16 v[54:57], v[222:225], v[166:169], v[54:57]
	v_mfma_f32_16x16x32_bf16 v[50:53], v[230:233], v[166:169], v[50:53]
	v_mfma_f32_16x16x32_bf16 v[38:41], v[222:225], v[174:177], v[38:41]
	v_mfma_f32_16x16x32_bf16 v[34:37], v[230:233], v[174:177], v[34:37]
	v_mfma_f32_16x16x32_bf16 v[22:25], v[222:225], v[182:185], v[22:25]
	v_mfma_f32_16x16x32_bf16 v[18:21], v[230:233], v[182:185], v[18:21]
	v_mfma_f32_16x16x32_bf16 v[6:9], v[222:225], v[190:193], v[6:9]
	v_mfma_f32_16x16x32_bf16 v[2:5], v[230:233], v[190:193], v[2:5]
	v_mfma_f32_16x16x32_bf16 v[54:57], v[226:229], v[170:173], v[54:57]
	v_mfma_f32_16x16x32_bf16 v[50:53], v[234:237], v[170:173], v[50:53]
	v_mfma_f32_16x16x32_bf16 v[38:41], v[226:229], v[178:181], v[38:41]
	v_mfma_f32_16x16x32_bf16 v[34:37], v[234:237], v[178:181], v[34:37]
	v_mfma_f32_16x16x32_bf16 v[22:25], v[226:229], v[186:189], v[22:25]
	v_mfma_f32_16x16x32_bf16 v[18:21], v[234:237], v[186:189], v[18:21]
	v_mfma_f32_16x16x32_bf16 v[6:9], v[226:229], v[194:197], v[6:9]
	v_mfma_f32_16x16x32_bf16 v[2:5], v[234:237], v[194:197], v[2:5]
	s_add_i32 s76, s76, 2
	s_add_u32 s56, s56, 0x100
	s_addc_u32 s57, s57, 0
	s_add_u32 s74, s74, 0x100
	s_addc_u32 s75, s75, 0
	s_cmp_gt_u32 s76, 13
	s_barrier
	s_cbranch_scc0 .LBB0_52
	v_lshl_add_u32 v154, s69, 10, v150
	ds_read2_b32 v[158:159], v154 offset1:16
	ds_read2_b32 v[160:161], v154 offset0:32 offset1:48
	s_lshl_b32 s31, s70, 8
	s_or_b32 s31, s31, s67
	s_ashr_i32 s31, s31, 1
	v_readlane_b32 s18, v253, 30
	v_readlane_b32 s19, v253, 31
	v_or_b32_e32 v146, s31, v151
	v_lshl_add_u32 v153, s71, 8, v148
	v_ashrrev_i32_e32 v147, 31, v146
	s_movk_i32 s4, 0x1600
	v_mov_b64_e32 v[144:145], s[18:19]
	v_lshlrev_b64 v[146:147], 1, v[146:147]
	v_mad_i64_i32 v[156:157], s[56:57], v153, s4, v[144:145]
	v_and_b32_e32 v144, 4, v151
	v_mul_u32_u24_e32 v144, 30, v144
	v_mov_b32_e32 v145, 0
	v_lshl_add_u64 v[156:157], v[156:157], 0, v[146:147]
	s_mov_b32 s70, s30
	s_mov_b32 s71, s50
	s_mov_b64 s[58:59], s[54:55]
	v_lshl_add_u64 v[156:157], v[156:157], 0, v[144:145]
	v_readlane_b32 s5, v253, 17
	v_readlane_b32 s6, v253, 18
	v_readlane_b32 s7, v253, 19
	v_readlane_b32 s8, v253, 20
	v_readlane_b32 s9, v253, 21
	v_readlane_b32 s10, v253, 22
	v_readlane_b32 s11, v253, 23
	v_readlane_b32 s12, v253, 24
	v_readlane_b32 s13, v253, 25
	v_readlane_b32 s14, v253, 26
	v_readlane_b32 s15, v253, 27
	v_readlane_b32 s16, v253, 28
	v_readlane_b32 s17, v253, 29
	s_mov_b32 s56, 0x16000
	s_mov_b32 s57, 0
	s_waitcnt lgkmcnt(0)
	v_pk_mul_f32 v[126:127], v[126:127], v[158:159] op_sel_hi:[1,0]
	v_pk_mul_f32 v[128:129], v[128:129], v[158:159] op_sel_hi:[1,0]
	v_pk_mul_f32 v[122:123], v[122:123], v[158:159] op_sel_hi:[1,0]
	v_pk_mul_f32 v[124:125], v[124:125], v[158:159] op_sel_hi:[1,0]
	v_mul_f32_e32 v144, 0xbfb8aa3b, v126
	v_mul_f32_e32 v145, 0xbfb8aa3b, v127
	v_mul_f32_e32 v146, 0xbfb8aa3b, v128
	v_mul_f32_e32 v147, 0xbfb8aa3b, v129
	v_exp_f32_e32 v144, v144
	v_exp_f32_e32 v145, v145
	v_exp_f32_e32 v146, v146
	v_exp_f32_e32 v147, v147
	v_add_f32_e32 v144, 1.0, v144
	v_add_f32_e32 v145, 1.0, v145
	v_add_f32_e32 v146, 1.0, v146
	v_add_f32_e32 v147, 1.0, v147
	v_rcp_f32_e32 v144, v144
	v_rcp_f32_e32 v145, v145
	v_rcp_f32_e32 v146, v146
	v_rcp_f32_e32 v147, v147
	v_pk_mul_f32 v[126:127], v[126:127], v[144:145]
	v_pk_mul_f32 v[128:129], v[128:129], v[146:147]
	v_pk_mul_f32 v[126:127], v[126:127], v[122:123]
	v_pk_mul_f32 v[128:129], v[128:129], v[124:125]
	v_cvt_pk_bf16_f32 v122, v126, v127
	v_cvt_pk_bf16_f32 v123, v128, v129
	v_pk_mul_f32 v[118:119], v[118:119], v[158:159] op_sel_hi:[1,0]
	v_pk_mul_f32 v[120:121], v[120:121], v[158:159] op_sel_hi:[1,0]
	v_pk_mul_f32 v[114:115], v[114:115], v[158:159] op_sel_hi:[1,0]
	v_pk_mul_f32 v[116:117], v[116:117], v[158:159] op_sel_hi:[1,0]
	v_pk_mul_f32 v[110:111], v[110:111], v[158:159] op_sel:[0,1]
	v_pk_mul_f32 v[112:113], v[112:113], v[158:159] op_sel:[0,1]
	v_pk_mul_f32 v[106:107], v[106:107], v[158:159] op_sel:[0,1]
	v_pk_mul_f32 v[108:109], v[108:109], v[158:159] op_sel:[0,1]
	v_mul_f32_e32 v144, 0xbfb8aa3b, v118
	v_mul_f32_e32 v145, 0xbfb8aa3b, v119
	v_mul_f32_e32 v146, 0xbfb8aa3b, v120
; DI unsigned pk2(float lo, float hi) { f32x2 v = {lo, hi}; bf2_t r = __builtin_convertvector(v, bf2_t); return __builtin_bit_cast(unsigned, r); }
; DI float silu(float x) { return x * __builtin_amdgcn_rcpf(1.f + __expf(-x)); }
; #define PG8_LAS __attribute__((address_space(3)))
;   DI void operator()(const f32x4 (&acc)[2][2][4][2], const Unit& u, int wr, int wc, int fr, int fq, const PG8_LAS float* sR) const {
;     const int row0 = u.pm * BM + wr * 64 + fr, j0 = (u.pn * BM + wc * 32) / 2 + 4 * fq;
; #pragma unroll
;     for (int ai = 0; ai < 2; ++ai)
; #pragma unroll
;       for (int m = 0; m < 4; ++m) {
;         bf16_t* rowp = Hd + (size_t)(row0 + ai * HALF + m * 16) * 2816 + j0;
;         const float rs = sR[ai * 128 + m * 16 + fr];
; #pragma unroll
;         for (int bj = 0; bj < 2; ++bj) {
;           const f32x4 g = acc[ai][bj][m][0] * rs, up = acc[ai][bj][m][1] * rs;
;           u32x2 o; o[0] = pk2(silu(g[0]) * up[0], silu(g[1]) * up[1]); o[1] = pk2(silu(g[2]) * up[2], silu(g[3]) * up[3]);
;           *(u32x2*)(rowp + bj * (HALF / 2)) = o;
;         }
;       }
	v_mul_f32_e32 v147, 0xbfb8aa3b, v121
	v_mul_f32_e32 v126, 0xbfb8aa3b, v110
	v_mul_f32_e32 v127, 0xbfb8aa3b, v111
	v_mul_f32_e32 v128, 0xbfb8aa3b, v112
	v_mul_f32_e32 v129, 0xbfb8aa3b, v113
	v_exp_f32_e32 v144, v144
	v_exp_f32_e32 v145, v145
	v_exp_f32_e32 v146, v146
	v_exp_f32_e32 v147, v147
	v_exp_f32_e32 v126, v126
	v_exp_f32_e32 v127, v127
	v_exp_f32_e32 v128, v128
	v_exp_f32_e32 v129, v129
	v_add_f32_e32 v144, 1.0, v144
	v_add_f32_e32 v145, 1.0, v145
	v_add_f32_e32 v146, 1.0, v146
	v_add_f32_e32 v147, 1.0, v147
	v_add_f32_e32 v126, 1.0, v126
	v_add_f32_e32 v127, 1.0, v127
	v_add_f32_e32 v128, 1.0, v128
	v_add_f32_e32 v129, 1.0, v129
	v_rcp_f32_e32 v144, v144
	v_rcp_f32_e32 v145, v145
	v_rcp_f32_e32 v146, v146
	v_rcp_f32_e32 v147, v147
	v_rcp_f32_e32 v126, v126
	v_rcp_f32_e32 v127, v127
	v_rcp_f32_e32 v128, v128
	v_rcp_f32_e32 v129, v129
	v_pk_mul_f32 v[118:119], v[118:119], v[144:145]
	v_pk_mul_f32 v[120:121], v[120:121], v[146:147]
	v_pk_mul_f32 v[110:111], v[110:111], v[126:127]
	v_pk_mul_f32 v[112:113], v[112:113], v[128:129]
	v_pk_mul_f32 v[118:119], v[118:119], v[114:115]
	v_pk_mul_f32 v[120:121], v[120:121], v[116:117]
	v_pk_mul_f32 v[110:111], v[110:111], v[106:107]
	v_pk_mul_f32 v[112:113], v[112:113], v[108:109]
	v_cvt_pk_bf16_f32 v124, v118, v119
	v_cvt_pk_bf16_f32 v125, v120, v121
	v_cvt_pk_bf16_f32 v106, v110, v111
	v_cvt_pk_bf16_f32 v107, v112, v113
	s_nop 1
	v_permlane16_swap_b32_e32 v122, v124
	v_permlane16_swap_b32_e32 v123, v125
	global_store_dwordx4 v[156:157], v[122:125], off
	v_lshl_add_u64 v[156:157], v[156:157], 0, s[56:57]
	ds_read2_b32 v[118:119], v154 offset0:128 offset1:144
	ds_read2_b32 v[120:121], v154 offset0:160 offset1:176
	v_pk_mul_f32 v[102:103], v[102:103], v[158:159] op_sel:[0,1]
	v_pk_mul_f32 v[104:105], v[104:105], v[158:159] op_sel:[0,1]
	v_pk_mul_f32 v[98:99], v[98:99], v[158:159] op_sel:[0,1]
	v_pk_mul_f32 v[100:101], v[100:101], v[158:159] op_sel:[0,1]
	v_pk_mul_f32 v[94:95], v[94:95], v[160:161] op_sel_hi:[1,0]
	v_pk_mul_f32 v[96:97], v[96:97], v[160:161] op_sel_hi:[1,0]
	v_pk_mul_f32 v[90:91], v[90:91], v[160:161] op_sel_hi:[1,0]
	v_pk_mul_f32 v[92:93], v[92:93], v[160:161] op_sel_hi:[1,0]
	v_mul_f32_e32 v144, 0xbfb8aa3b, v102
	v_mul_f32_e32 v145, 0xbfb8aa3b, v103
	v_mul_f32_e32 v146, 0xbfb8aa3b, v104
	v_mul_f32_e32 v147, 0xbfb8aa3b, v105
	v_mul_f32_e32 v126, 0xbfb8aa3b, v94
	v_mul_f32_e32 v127, 0xbfb8aa3b, v95
	v_mul_f32_e32 v128, 0xbfb8aa3b, v96
	v_mul_f32_e32 v129, 0xbfb8aa3b, v97
	v_exp_f32_e32 v144, v144
	v_exp_f32_e32 v145, v145
	v_exp_f32_e32 v146, v146
	v_exp_f32_e32 v147, v147
	v_exp_f32_e32 v126, v126
	v_exp_f32_e32 v127, v127
	v_exp_f32_e32 v128, v128
	v_exp_f32_e32 v129, v129
	v_add_f32_e32 v144, 1.0, v144
	v_add_f32_e32 v145, 1.0, v145
	v_add_f32_e32 v146, 1.0, v146
	v_add_f32_e32 v147, 1.0, v147
	v_add_f32_e32 v126, 1.0, v126
	v_add_f32_e32 v127, 1.0, v127
	v_add_f32_e32 v128, 1.0, v128
	v_add_f32_e32 v129, 1.0, v129
	v_rcp_f32_e32 v144, v144
	v_rcp_f32_e32 v145, v145
	v_rcp_f32_e32 v146, v146
	v_rcp_f32_e32 v147, v147
	v_rcp_f32_e32 v126, v126
	v_rcp_f32_e32 v127, v127
	v_rcp_f32_e32 v128, v128
	v_rcp_f32_e32 v129, v129
	v_pk_mul_f32 v[102:103], v[102:103], v[144:145]
	v_pk_mul_f32 v[104:105], v[104:105], v[146:147]
	v_pk_mul_f32 v[94:95], v[94:95], v[126:127]
	v_pk_mul_f32 v[96:97], v[96:97], v[128:129]
	v_pk_mul_f32 v[102:103], v[102:103], v[98:99]
	v_pk_mul_f32 v[104:105], v[104:105], v[100:101]
	v_pk_mul_f32 v[94:95], v[94:95], v[90:91]
	v_pk_mul_f32 v[96:97], v[96:97], v[92:93]
	v_cvt_pk_bf16_f32 v108, v102, v103
	v_cvt_pk_bf16_f32 v109, v104, v105
	v_cvt_pk_bf16_f32 v90, v94, v95
	v_cvt_pk_bf16_f32 v91, v96, v97
	s_nop 1
	v_permlane16_swap_b32_e32 v106, v108
	v_permlane16_swap_b32_e32 v107, v109
	global_store_dwordx4 v[156:157], v[106:109], off
	v_lshl_add_u64 v[156:157], v[156:157], 0, s[56:57]
	v_pk_mul_f32 v[86:87], v[86:87], v[160:161] op_sel_hi:[1,0]
	v_pk_mul_f32 v[88:89], v[88:89], v[160:161] op_sel_hi:[1,0]
	v_pk_mul_f32 v[82:83], v[82:83], v[160:161] op_sel_hi:[1,0]
	v_pk_mul_f32 v[84:85], v[84:85], v[160:161] op_sel_hi:[1,0]
	v_pk_mul_f32 v[78:79], v[78:79], v[160:161] op_sel:[0,1]
	v_pk_mul_f32 v[80:81], v[80:81], v[160:161] op_sel:[0,1]
	v_pk_mul_f32 v[74:75], v[74:75], v[160:161] op_sel:[0,1]
	v_pk_mul_f32 v[76:77], v[76:77], v[160:161] op_sel:[0,1]
	v_mul_f32_e32 v144, 0xbfb8aa3b, v86
	v_mul_f32_e32 v145, 0xbfb8aa3b, v87
	v_mul_f32_e32 v146, 0xbfb8aa3b, v88
	v_mul_f32_e32 v147, 0xbfb8aa3b, v89
	v_mul_f32_e32 v126, 0xbfb8aa3b, v78
	v_mul_f32_e32 v127, 0xbfb8aa3b, v79
	v_mul_f32_e32 v128, 0xbfb8aa3b, v80
	v_mul_f32_e32 v129, 0xbfb8aa3b, v81
	v_exp_f32_e32 v144, v144
	v_exp_f32_e32 v145, v145
	v_exp_f32_e32 v146, v146
	v_exp_f32_e32 v147, v147
	v_exp_f32_e32 v126, v126
	v_exp_f32_e32 v127, v127
	v_exp_f32_e32 v128, v128
	v_exp_f32_e32 v129, v129
	v_add_f32_e32 v144, 1.0, v144
	v_add_f32_e32 v145, 1.0, v145
	v_add_f32_e32 v146, 1.0, v146
	v_add_f32_e32 v147, 1.0, v147
	v_add_f32_e32 v126, 1.0, v126
	v_add_f32_e32 v127, 1.0, v127
	v_add_f32_e32 v128, 1.0, v128
	v_add_f32_e32 v129, 1.0, v129
	v_rcp_f32_e32 v144, v144
	v_rcp_f32_e32 v145, v145
	v_rcp_f32_e32 v146, v146
	v_rcp_f32_e32 v147, v147
	v_rcp_f32_e32 v126, v126
	v_rcp_f32_e32 v127, v127
	v_rcp_f32_e32 v128, v128
	v_rcp_f32_e32 v129, v129
	v_pk_mul_f32 v[86:87], v[86:87], v[144:145]
	v_pk_mul_f32 v[88:89], v[88:89], v[146:147]
	v_pk_mul_f32 v[78:79], v[78:79], v[126:127]
	v_pk_mul_f32 v[80:81], v[80:81], v[128:129]
	v_pk_mul_f32 v[86:87], v[86:87], v[82:83]
	v_pk_mul_f32 v[88:89], v[88:89], v[84:85]
	v_pk_mul_f32 v[78:79], v[78:79], v[74:75]
	v_pk_mul_f32 v[80:81], v[80:81], v[76:77]
	v_cvt_pk_bf16_f32 v92, v86, v87
	v_cvt_pk_bf16_f32 v93, v88, v89
	v_cvt_pk_bf16_f32 v74, v78, v79
	v_cvt_pk_bf16_f32 v75, v80, v81
	s_nop 1
	v_permlane16_swap_b32_e32 v90, v92
	v_permlane16_swap_b32_e32 v91, v93
	global_store_dwordx4 v[156:157], v[90:93], off
	v_lshl_add_u64 v[156:157], v[156:157], 0, s[56:57]
	s_waitcnt lgkmcnt(0)
; DI unsigned pk2(float lo, float hi) { f32x2 v = {lo, hi}; bf2_t r = __builtin_convertvector(v, bf2_t); return __builtin_bit_cast(unsigned, r); }
; DI float silu(float x) { return x * __builtin_amdgcn_rcpf(1.f + __expf(-x)); }
; #define PG8_LAS __attribute__((address_space(3)))
;   DI void operator()(const f32x4 (&acc)[2][2][4][2], const Unit& u, int wr, int wc, int fr, int fq, const PG8_LAS float* sR) const {
;     const int row0 = u.pm * BM + wr * 64 + fr, j0 = (u.pn * BM + wc * 32) / 2 + 4 * fq;
; #pragma unroll
;     for (int ai = 0; ai < 2; ++ai)
; #pragma unroll
;       for (int m = 0; m < 4; ++m) {
;         bf16_t* rowp = Hd + (size_t)(row0 + ai * HALF + m * 16) * 2816 + j0;
;         const float rs = sR[ai * 128 + m * 16 + fr];
; #pragma unroll
;         for (int bj = 0; bj < 2; ++bj) {
;           const f32x4 g = acc[ai][bj][m][0] * rs, up = acc[ai][bj][m][1] * rs;
;           u32x2 o; o[0] = pk2(silu(g[0]) * up[0], silu(g[1]) * up[1]); o[1] = pk2(silu(g[2]) * up[2], silu(g[3]) * up[3]);
;           *(u32x2*)(rowp + bj * (HALF / 2)) = o;
;         }
;       }
	v_pk_mul_f32 v[70:71], v[70:71], v[160:161] op_sel:[0,1]
	v_pk_mul_f32 v[72:73], v[72:73], v[160:161] op_sel:[0,1]
	v_pk_mul_f32 v[66:67], v[66:67], v[160:161] op_sel:[0,1]
	v_pk_mul_f32 v[68:69], v[68:69], v[160:161] op_sel:[0,1]
	v_pk_mul_f32 v[62:63], v[62:63], v[118:119] op_sel_hi:[1,0]
	v_pk_mul_f32 v[64:65], v[64:65], v[118:119] op_sel_hi:[1,0]
	v_pk_mul_f32 v[58:59], v[58:59], v[118:119] op_sel_hi:[1,0]
	v_pk_mul_f32 v[60:61], v[60:61], v[118:119] op_sel_hi:[1,0]
	v_mul_f32_e32 v144, 0xbfb8aa3b, v70
	v_mul_f32_e32 v145, 0xbfb8aa3b, v71
	v_mul_f32_e32 v146, 0xbfb8aa3b, v72
	v_mul_f32_e32 v147, 0xbfb8aa3b, v73
	v_mul_f32_e32 v126, 0xbfb8aa3b, v62
	v_mul_f32_e32 v127, 0xbfb8aa3b, v63
	v_mul_f32_e32 v128, 0xbfb8aa3b, v64
	v_mul_f32_e32 v129, 0xbfb8aa3b, v65
	v_exp_f32_e32 v144, v144
	v_exp_f32_e32 v145, v145
	v_exp_f32_e32 v146, v146
	v_exp_f32_e32 v147, v147
	v_exp_f32_e32 v126, v126
	v_exp_f32_e32 v127, v127
	v_exp_f32_e32 v128, v128
	v_exp_f32_e32 v129, v129
	v_add_f32_e32 v144, 1.0, v144
	v_add_f32_e32 v145, 1.0, v145
	v_add_f32_e32 v146, 1.0, v146
	v_add_f32_e32 v147, 1.0, v147
	v_add_f32_e32 v126, 1.0, v126
	v_add_f32_e32 v127, 1.0, v127
	v_add_f32_e32 v128, 1.0, v128
	v_add_f32_e32 v129, 1.0, v129
	v_rcp_f32_e32 v144, v144
	v_rcp_f32_e32 v145, v145
	v_rcp_f32_e32 v146, v146
	v_rcp_f32_e32 v147, v147
	v_rcp_f32_e32 v126, v126
	v_rcp_f32_e32 v127, v127
	v_rcp_f32_e32 v128, v128
	v_rcp_f32_e32 v129, v129
	v_pk_mul_f32 v[70:71], v[70:71], v[144:145]
	v_pk_mul_f32 v[72:73], v[72:73], v[146:147]
	v_pk_mul_f32 v[62:63], v[62:63], v[126:127]
	v_pk_mul_f32 v[64:65], v[64:65], v[128:129]
	v_pk_mul_f32 v[70:71], v[70:71], v[66:67]
	v_pk_mul_f32 v[72:73], v[72:73], v[68:69]
	v_pk_mul_f32 v[62:63], v[62:63], v[58:59]
	v_pk_mul_f32 v[64:65], v[64:65], v[60:61]
	v_cvt_pk_bf16_f32 v76, v70, v71
	v_cvt_pk_bf16_f32 v77, v72, v73
	v_cvt_pk_bf16_f32 v58, v62, v63
	v_cvt_pk_bf16_f32 v59, v64, v65
	s_nop 1
	v_permlane16_swap_b32_e32 v74, v76
	v_permlane16_swap_b32_e32 v75, v77
	global_store_dwordx4 v[156:157], v[74:77], off
	s_mov_b32 s56, 0x6e000
	v_lshl_add_u64 v[156:157], v[156:157], 0, s[56:57]
	s_mov_b32 s56, 0x16000
	v_pk_mul_f32 v[54:55], v[54:55], v[118:119] op_sel_hi:[1,0]
	v_pk_mul_f32 v[56:57], v[56:57], v[118:119] op_sel_hi:[1,0]
	v_pk_mul_f32 v[50:51], v[50:51], v[118:119] op_sel_hi:[1,0]
	v_pk_mul_f32 v[52:53], v[52:53], v[118:119] op_sel_hi:[1,0]
	v_pk_mul_f32 v[46:47], v[46:47], v[118:119] op_sel:[0,1]
	v_pk_mul_f32 v[48:49], v[48:49], v[118:119] op_sel:[0,1]
	v_pk_mul_f32 v[42:43], v[42:43], v[118:119] op_sel:[0,1]
	v_pk_mul_f32 v[44:45], v[44:45], v[118:119] op_sel:[0,1]
	v_mul_f32_e32 v144, 0xbfb8aa3b, v54
	v_mul_f32_e32 v145, 0xbfb8aa3b, v55
	v_mul_f32_e32 v146, 0xbfb8aa3b, v56
	v_mul_f32_e32 v147, 0xbfb8aa3b, v57
	v_mul_f32_e32 v126, 0xbfb8aa3b, v46
	v_mul_f32_e32 v127, 0xbfb8aa3b, v47
	v_mul_f32_e32 v128, 0xbfb8aa3b, v48
	v_mul_f32_e32 v129, 0xbfb8aa3b, v49
	v_exp_f32_e32 v144, v144
	v_exp_f32_e32 v145, v145
	v_exp_f32_e32 v146, v146
	v_exp_f32_e32 v147, v147
	v_exp_f32_e32 v126, v126
	v_exp_f32_e32 v127, v127
	v_exp_f32_e32 v128, v128
	v_exp_f32_e32 v129, v129
	v_add_f32_e32 v144, 1.0, v144
	v_add_f32_e32 v145, 1.0, v145
	v_add_f32_e32 v146, 1.0, v146
	v_add_f32_e32 v147, 1.0, v147
	v_add_f32_e32 v126, 1.0, v126
	v_add_f32_e32 v127, 1.0, v127
	v_add_f32_e32 v128, 1.0, v128
	v_add_f32_e32 v129, 1.0, v129
	v_rcp_f32_e32 v144, v144
	v_rcp_f32_e32 v145, v145
	v_rcp_f32_e32 v146, v146
	v_rcp_f32_e32 v147, v147
	v_rcp_f32_e32 v126, v126
	v_rcp_f32_e32 v127, v127
	v_rcp_f32_e32 v128, v128
	v_rcp_f32_e32 v129, v129
	v_pk_mul_f32 v[54:55], v[54:55], v[144:145]
	v_pk_mul_f32 v[56:57], v[56:57], v[146:147]
	v_pk_mul_f32 v[46:47], v[46:47], v[126:127]
	v_pk_mul_f32 v[48:49], v[48:49], v[128:129]
	v_pk_mul_f32 v[54:55], v[54:55], v[50:51]
	v_pk_mul_f32 v[56:57], v[56:57], v[52:53]
	v_pk_mul_f32 v[46:47], v[46:47], v[42:43]
	v_pk_mul_f32 v[48:49], v[48:49], v[44:45]
	v_cvt_pk_bf16_f32 v60, v54, v55
	v_cvt_pk_bf16_f32 v61, v56, v57
	v_cvt_pk_bf16_f32 v42, v46, v47
	v_cvt_pk_bf16_f32 v43, v48, v49
	s_nop 1
	v_permlane16_swap_b32_e32 v58, v60
	v_permlane16_swap_b32_e32 v59, v61
	global_store_dwordx4 v[156:157], v[58:61], off
	v_lshl_add_u64 v[156:157], v[156:157], 0, s[56:57]
	v_pk_mul_f32 v[38:39], v[38:39], v[118:119] op_sel:[0,1]
	v_pk_mul_f32 v[40:41], v[40:41], v[118:119] op_sel:[0,1]
	v_pk_mul_f32 v[34:35], v[34:35], v[118:119] op_sel:[0,1]
	v_pk_mul_f32 v[36:37], v[36:37], v[118:119] op_sel:[0,1]
	v_pk_mul_f32 v[30:31], v[30:31], v[120:121] op_sel_hi:[1,0]
	v_pk_mul_f32 v[32:33], v[32:33], v[120:121] op_sel_hi:[1,0]
	v_pk_mul_f32 v[26:27], v[26:27], v[120:121] op_sel_hi:[1,0]
	v_pk_mul_f32 v[28:29], v[28:29], v[120:121] op_sel_hi:[1,0]
	v_mul_f32_e32 v144, 0xbfb8aa3b, v38
	v_mul_f32_e32 v145, 0xbfb8aa3b, v39
	v_mul_f32_e32 v146, 0xbfb8aa3b, v40
; DI unsigned pk2(float lo, float hi) { f32x2 v = {lo, hi}; bf2_t r = __builtin_convertvector(v, bf2_t); return __builtin_bit_cast(unsigned, r); }
; DI float silu(float x) { return x * __builtin_amdgcn_rcpf(1.f + __expf(-x)); }
; #define PG8_WAIT_V(n) asm volatile("s_waitcnt vmcnt(" #n ")" ::: "memory")
; #define PG8_BAR __builtin_amdgcn_s_barrier()
;   DI void operator()(const f32x4 (&acc)[2][2][4][2], const Unit& u, int wr, int wc, int fr, int fq, const PG8_LAS float* sR) const {
;     ...
;     for (int ai = 0; ai < 2; ++ai)
; #pragma unroll
;       for (int m = 0; m < 4; ++m) {
;         bf16_t* rowp = Hd + (size_t)(row0 + ai * HALF + m * 16) * 2816 + j0;
;         const float rs = sR[ai * 128 + m * 16 + fr];
; #pragma unroll
;         for (int bj = 0; bj < 2; ++bj) {
;           const f32x4 g = acc[ai][bj][m][0] * rs, up = acc[ai][bj][m][1] * rs;
;           u32x2 o; o[0] = pk2(silu(g[0]) * up[0], silu(g[1]) * up[1]); o[1] = pk2(silu(g[2]) * up[2], silu(g[3]) * up[3]);
;           *(u32x2*)(rowp + bj * (HALF / 2)) = o;
;         }
;       }
; template <class Epi>
; DI void gemm_phase(PG8_LAS unsigned char* lds, const Gemm g, const StaticOrder& S, const Epi& E) {
;     ...
;     if (!has_next) break;
; #pragma unroll
;     for (int a = 0; a < 2; ++a)
; #pragma unroll
;       for (int b = 0; b < 2; ++b)
; #pragma unroll
;         for (int m = 0; m < 4; ++m)
; #pragma unroll
;           for (int n = 0; n < 2; ++n) acc[a][b][m][n] = (f32x4){0.f, 0.f, 0.f, 0.f};
;     cur = nxt; cA = nA; cB = nB; ++ui;
;   }
;   PG8_WAIT_V(0);
;   if (wr == 0) PG8_BAR;
;   PG8_BAR;
	v_mul_f32_e32 v147, 0xbfb8aa3b, v41
	v_mul_f32_e32 v126, 0xbfb8aa3b, v30
	v_mul_f32_e32 v127, 0xbfb8aa3b, v31
	v_mul_f32_e32 v128, 0xbfb8aa3b, v32
	v_mul_f32_e32 v129, 0xbfb8aa3b, v33
	v_exp_f32_e32 v144, v144
	v_exp_f32_e32 v145, v145
	v_exp_f32_e32 v146, v146
	v_exp_f32_e32 v147, v147
	v_exp_f32_e32 v126, v126
	v_exp_f32_e32 v127, v127
	v_exp_f32_e32 v128, v128
	v_exp_f32_e32 v129, v129
	v_add_f32_e32 v144, 1.0, v144
	v_add_f32_e32 v145, 1.0, v145
	v_add_f32_e32 v146, 1.0, v146
	v_add_f32_e32 v147, 1.0, v147
	v_add_f32_e32 v126, 1.0, v126
	v_add_f32_e32 v127, 1.0, v127
	v_add_f32_e32 v128, 1.0, v128
	v_add_f32_e32 v129, 1.0, v129
	v_rcp_f32_e32 v144, v144
	v_rcp_f32_e32 v145, v145
	v_rcp_f32_e32 v146, v146
	v_rcp_f32_e32 v147, v147
	v_rcp_f32_e32 v126, v126
	v_rcp_f32_e32 v127, v127
	v_rcp_f32_e32 v128, v128
	v_rcp_f32_e32 v129, v129
	v_pk_mul_f32 v[38:39], v[38:39], v[144:145]
	v_pk_mul_f32 v[40:41], v[40:41], v[146:147]
	v_pk_mul_f32 v[30:31], v[30:31], v[126:127]
	v_pk_mul_f32 v[32:33], v[32:33], v[128:129]
	v_pk_mul_f32 v[38:39], v[38:39], v[34:35]
	v_pk_mul_f32 v[40:41], v[40:41], v[36:37]
	v_pk_mul_f32 v[30:31], v[30:31], v[26:27]
	v_pk_mul_f32 v[32:33], v[32:33], v[28:29]
	v_cvt_pk_bf16_f32 v44, v38, v39
	v_cvt_pk_bf16_f32 v45, v40, v41
	v_cvt_pk_bf16_f32 v26, v30, v31
	v_cvt_pk_bf16_f32 v27, v32, v33
	s_nop 1
	v_permlane16_swap_b32_e32 v42, v44
	v_permlane16_swap_b32_e32 v43, v45
	global_store_dwordx4 v[156:157], v[42:45], off
	v_lshl_add_u64 v[156:157], v[156:157], 0, s[56:57]
	v_pk_mul_f32 v[22:23], v[22:23], v[120:121] op_sel_hi:[1,0]
	v_pk_mul_f32 v[24:25], v[24:25], v[120:121] op_sel_hi:[1,0]
	v_pk_mul_f32 v[18:19], v[18:19], v[120:121] op_sel_hi:[1,0]
	v_pk_mul_f32 v[20:21], v[20:21], v[120:121] op_sel_hi:[1,0]
	v_pk_mul_f32 v[14:15], v[14:15], v[120:121] op_sel:[0,1]
	v_pk_mul_f32 v[16:17], v[16:17], v[120:121] op_sel:[0,1]
	v_pk_mul_f32 v[10:11], v[10:11], v[120:121] op_sel:[0,1]
	v_pk_mul_f32 v[12:13], v[12:13], v[120:121] op_sel:[0,1]
	v_mul_f32_e32 v144, 0xbfb8aa3b, v22
	v_mul_f32_e32 v145, 0xbfb8aa3b, v23
	v_mul_f32_e32 v146, 0xbfb8aa3b, v24
	v_mul_f32_e32 v147, 0xbfb8aa3b, v25
	v_mul_f32_e32 v126, 0xbfb8aa3b, v14
	v_mul_f32_e32 v127, 0xbfb8aa3b, v15
	v_mul_f32_e32 v128, 0xbfb8aa3b, v16
	v_mul_f32_e32 v129, 0xbfb8aa3b, v17
	v_exp_f32_e32 v144, v144
	v_exp_f32_e32 v145, v145
	v_exp_f32_e32 v146, v146
	v_exp_f32_e32 v147, v147
	v_exp_f32_e32 v126, v126
	v_exp_f32_e32 v127, v127
	v_exp_f32_e32 v128, v128
	v_exp_f32_e32 v129, v129
	v_add_f32_e32 v144, 1.0, v144
	v_add_f32_e32 v145, 1.0, v145
	v_add_f32_e32 v146, 1.0, v146
	v_add_f32_e32 v147, 1.0, v147
	v_add_f32_e32 v126, 1.0, v126
	v_add_f32_e32 v127, 1.0, v127
	v_add_f32_e32 v128, 1.0, v128
	v_add_f32_e32 v129, 1.0, v129
	v_rcp_f32_e32 v144, v144
	v_rcp_f32_e32 v145, v145
	v_rcp_f32_e32 v146, v146
	v_rcp_f32_e32 v147, v147
	v_rcp_f32_e32 v126, v126
	v_rcp_f32_e32 v127, v127
	v_rcp_f32_e32 v128, v128
	v_rcp_f32_e32 v129, v129
	v_pk_mul_f32 v[22:23], v[22:23], v[144:145]
	v_pk_mul_f32 v[24:25], v[24:25], v[146:147]
	v_pk_mul_f32 v[14:15], v[14:15], v[126:127]
	v_pk_mul_f32 v[16:17], v[16:17], v[128:129]
	v_pk_mul_f32 v[22:23], v[22:23], v[18:19]
	v_pk_mul_f32 v[24:25], v[24:25], v[20:21]
	v_pk_mul_f32 v[14:15], v[14:15], v[10:11]
	v_pk_mul_f32 v[16:17], v[16:17], v[12:13]
	v_cvt_pk_bf16_f32 v28, v22, v23
	v_cvt_pk_bf16_f32 v29, v24, v25
	v_cvt_pk_bf16_f32 v10, v14, v15
	v_cvt_pk_bf16_f32 v11, v16, v17
	s_nop 1
	v_permlane16_swap_b32_e32 v26, v28
	v_permlane16_swap_b32_e32 v27, v29
	global_store_dwordx4 v[156:157], v[26:29], off
	v_lshl_add_u64 v[156:157], v[156:157], 0, s[56:57]
	v_pk_mul_f32 v[6:7], v[6:7], v[120:121] op_sel:[0,1]
	v_pk_mul_f32 v[8:9], v[8:9], v[120:121] op_sel:[0,1]
	v_pk_mul_f32 v[2:3], v[2:3], v[120:121] op_sel:[0,1]
	v_pk_mul_f32 v[4:5], v[4:5], v[120:121] op_sel:[0,1]
	v_mul_f32_e32 v144, 0xbfb8aa3b, v6
	v_mul_f32_e32 v145, 0xbfb8aa3b, v7
	v_mul_f32_e32 v146, 0xbfb8aa3b, v8
	v_mul_f32_e32 v147, 0xbfb8aa3b, v9
	v_exp_f32_e32 v144, v144
	v_exp_f32_e32 v145, v145
	v_exp_f32_e32 v146, v146
	v_exp_f32_e32 v147, v147
	v_add_f32_e32 v144, 1.0, v144
	v_add_f32_e32 v145, 1.0, v145
	v_add_f32_e32 v146, 1.0, v146
	v_add_f32_e32 v147, 1.0, v147
	v_rcp_f32_e32 v144, v144
	v_rcp_f32_e32 v145, v145
	v_rcp_f32_e32 v146, v146
	v_rcp_f32_e32 v147, v147
	v_pk_mul_f32 v[6:7], v[6:7], v[144:145]
	v_pk_mul_f32 v[8:9], v[8:9], v[146:147]
	v_pk_mul_f32 v[6:7], v[6:7], v[2:3]
	v_pk_mul_f32 v[8:9], v[8:9], v[4:5]
	v_cvt_pk_bf16_f32 v12, v6, v7
	v_cvt_pk_bf16_f32 v13, v8, v9
	s_nop 1
	v_permlane16_swap_b32_e32 v10, v12
	v_permlane16_swap_b32_e32 v11, v13
	global_store_dwordx4 v[156:157], v[10:13], off
	s_mov_b32 s69, s68
	s_mov_b64 s[56:57], s[52:53]
	s_and_b64 vcc, exec, s[40:41]
	s_cbranch_vccz .LBB0_49
	s_waitcnt vmcnt(0)
	s_cmpk_gt_u32 s28, 0xff
	s_cbranch_scc1 .LBB0_56
	s_barrier
